# v039 + HGRN: 16 prefetch loads use saddr form (running SGPR row base + per-lane 32-bit offsets; 32 address VALU per chunk removed) and 7 adjacent v_mul pairs packed
# baseline (speedup 1.0000x reference)
; #define LAS __attribute__((address_space(3)))
; __device__ __forceinline__ float bflo(unsigned u) { return __uint_as_float(u << 16); }
; __device__ __forceinline__ float bfhi(unsigned u) { return __uint_as_float(u & 0xffff0000u); }
; #define HG_LOAD(c_, q_, k_, v_) do { _Pragma("unroll") for (int j = 0; j < 8; ++j) { const size_t off = (tok0 + HG_TOK(c_, 8 * wid + j)) * 512 + hh * 128 + 2 * lane; \
;         q_[j] = *(const unsigned*)(QR + off); k_[j] = *(const unsigned*)(KK + off); } \
;         v_ = *(const u32x4*)(IR + (tok0 + HG_TOK(c_, tv)) * 512 + hh * 128 + dvh * 64 + cv * 8); } while (0)
; __device__ __forceinline__ void hgrn_phase(LAS unsigned char* lds, const bf16_t* mix, bf16_t* OFB, int item) {
;     ...
;     HG_LOAD(0, cq, ck, cvv);
;     __syncthreads();
;     for (int c = 0; c < 64; ++c) {
;         float c0[8], c1[8];
;         { float a0 = 1.f, a1 = 1.f;
; #pragma unroll
;           for (int j = 0; j < 8; ++j) { a0 *= 1.0f - bflo(ck[j]); a1 *= 1.0f - bfhi(ck[j]); c0[j] = a0; c1[j] = a1; } }
;         *(LAS f32x2*)(lds + HG_SEG + (wid * 128 + 2 * lane) * 4) = (f32x2){c0[7], c1[7]};
;         unsigned nq[8], nk[8]; u32x4 nv;
;         { const int cn = (c + 1 < 64) ? c + 1 : 63; HG_LOAD(cn, nq, nk, nv); }
.LBB0_507:
	s_and_b64 s[100:101], s[4:5], exec
	s_movk_i32 s100, 0x400
	s_cselect_b32 s98, s100, 0xfffffc00
	s_cselect_b32 s99, 0, -1
	s_add_i32 s74, s78, 1
	s_cmp_lg_u32 s78, 63
	s_cselect_b32 s92, s74, 63
	s_lshl_b32 s75, s92, 6
	s_add_i32 s93, s75, s33
	s_sub_i32 vcc_lo, 0xfff, s93
	s_and_b64 s[56:57], s[4:5], exec
	s_cselect_b32 s56, s93, vcc_lo
	s_ashr_i32 s57, s56, 31
	s_add_u32 s56, s90, s56
	s_addc_u32 s57, s91, s57
	s_lshl_b64 s[56:57], s[56:57], 10
	s_add_u32 s56, s56, s82
	s_addc_u32 s57, s57, s83
	s_sub_u32 s100, s88, s82
	v_add_u32_e32 v140, s100, v80
	s_waitcnt vmcnt(15)
	v_lshlrev_b32_e32 v36, 16, v75
	v_and_b32_e32 v37, 0xffff0000, v75
	s_waitcnt vmcnt(13)
	v_lshlrev_b32_e32 v34, 16, v76
	v_and_b32_e32 v35, 0xffff0000, v76
	s_waitcnt vmcnt(11)
	v_lshlrev_b32_e32 v32, 16, v77
	v_and_b32_e32 v33, 0xffff0000, v77
	s_waitcnt vmcnt(9)
	v_lshlrev_b32_e32 v14, 16, v78
	v_and_b32_e32 v15, 0xffff0000, v78
	global_load_dword v92, v80, s[56:57]
	global_load_dword v75, v140, s[56:57]
	s_add_u32 s56, s56, s98
	s_addc_u32 s57, s57, s99
	global_load_dword v93, v80, s[56:57]
	global_load_dword v76, v140, s[56:57]
	s_add_u32 s56, s56, s98
	s_addc_u32 s57, s57, s99
	global_load_dword v94, v80, s[56:57]
	global_load_dword v77, v140, s[56:57]
	s_add_u32 s56, s56, s98
	s_addc_u32 s57, s57, s99
	global_load_dword v95, v80, s[56:57]
	global_load_dword v78, v140, s[56:57]
	s_add_u32 s56, s56, s98
	s_addc_u32 s57, s57, s99
	s_waitcnt vmcnt(15)
	v_lshlrev_b32_e32 v12, 16, v89
	v_and_b32_e32 v13, 0xffff0000, v89
	s_waitcnt vmcnt(13)
	v_lshlrev_b32_e32 v10, 16, v90
	v_and_b32_e32 v11, 0xffff0000, v90
	s_waitcnt vmcnt(11)
	v_lshlrev_b32_e32 v8, 16, v91
	v_and_b32_e32 v9, 0xffff0000, v91
	s_waitcnt vmcnt(9)
	v_lshlrev_b32_e32 v6, 16, v88
	v_and_b32_e32 v7, 0xffff0000, v88
	global_load_dword v96, v80, s[56:57]
	global_load_dword v89, v140, s[56:57]
	s_add_u32 s56, s56, s98
	s_addc_u32 s57, s57, s99
	global_load_dword v97, v80, s[56:57]
	global_load_dword v90, v140, s[56:57]
	s_add_u32 s56, s56, s98
	s_addc_u32 s57, s57, s99
	global_load_dword v98, v80, s[56:57]
	global_load_dword v91, v140, s[56:57]
	s_add_u32 s56, s56, s98
	s_addc_u32 s57, s57, s99
	global_load_dword v99, v80, s[56:57]
	global_load_dword v88, v140, s[56:57]
	v_pk_add_f32 v[64:65], v[36:37], 1.0 op_sel_hi:[1,0] neg_lo:[1,0] neg_hi:[1,0]
	v_pk_add_f32 v[38:39], v[34:35], 1.0 op_sel_hi:[1,0] neg_lo:[1,0] neg_hi:[1,0]
	v_add_u32_e32 v44, s79, v69
	v_pk_mul_f32 v[62:63], v[64:65], v[38:39]
	v_pk_add_f32 v[38:39], v[32:33], 1.0 op_sel_hi:[1,0] neg_lo:[1,0] neg_hi:[1,0]
	s_andn2_b64 vcc, exec, s[64:65]
	v_pk_mul_f32 v[60:61], v[62:63], v[38:39]
	v_pk_add_f32 v[38:39], v[14:15], 1.0 op_sel_hi:[1,0] neg_lo:[1,0] neg_hi:[1,0]
	s_mov_b64 s[56:57], -1
	v_pk_mul_f32 v[58:59], v[60:61], v[38:39]
	v_pk_add_f32 v[38:39], v[12:13], 1.0 op_sel_hi:[1,0] neg_lo:[1,0] neg_hi:[1,0]
	s_nop 0
	v_pk_mul_f32 v[46:47], v[58:59], v[38:39]
	v_pk_add_f32 v[38:39], v[10:11], 1.0 op_sel_hi:[1,0] neg_lo:[1,0] neg_hi:[1,0]
	s_nop 0
	v_pk_mul_f32 v[42:43], v[46:47], v[38:39]
	v_pk_add_f32 v[38:39], v[8:9], 1.0 op_sel_hi:[1,0] neg_lo:[1,0] neg_hi:[1,0]
	s_nop 0
	v_pk_mul_f32 v[40:41], v[42:43], v[38:39]
	v_pk_add_f32 v[38:39], v[6:7], 1.0 op_sel_hi:[1,0] neg_lo:[1,0] neg_hi:[1,0]
	s_nop 0
	v_pk_mul_f32 v[38:39], v[40:41], v[38:39]
	ds_write_b64 v44, v[38:39]
	s_cbranch_vccnz .LBB0_509
	v_lshl_add_u32 v44, s92, 6, v68
	v_sub_u32_e32 v44, 0xfff, v44
	s_mov_b64 s[56:57], 0

; #define LAS __attribute__((address_space(3)))
; #define HG_BAR() asm volatile("s_waitcnt lgkmcnt(0)\n\ts_barrier" ::: "memory")
; __device__ __forceinline__ void hgrn_phase(LAS unsigned char* lds, const bf16_t* mix, bf16_t* OFB, int item) {
;     ...
;         HG_BAR();
;         float pre0 = 1.f, pre1 = 1.f, mid0 = 1.f, mid1 = 1.f, last0 = 1.f, last1 = 1.f;
; #pragma unroll
;         for (int s = 0; s < 8; ++s) { const f32x2 tt = *(LAS const f32x2*)(lds + HG_SEG + (s * 128 + 2 * lane) * 4);
;             pre0 *= (s < wid) ? tt[0] : 1.f; pre1 *= (s < wid) ? tt[1] : 1.f; if (s < 4) { mid0 *= tt[0]; mid1 *= tt[1]; } last0 *= tt[0]; last1 *= tt[1]; }
;         const float rm0 = __builtin_amdgcn_rcpf(mid0), rm1 = __builtin_amdgcn_rcpf(mid1);
;         const float eM0 = mid0, eM1 = mid1, eL0 = last0 * rm0, eL1 = last1 * rm1, pr0 = pre0 * rm0, pr1 = pre1 * rm1;
.LBB0_511:
	v_ashrrev_i32_e32 v45, 31, v44
	v_lshl_add_u64 v[44:45], s[90:91], 0, v[44:45]
	v_lshlrev_b64 v[44:45], 10, v[44:45]
	v_lshl_add_u64 v[44:45], v[52:53], 0, v[44:45]
	global_load_dwordx4 v[48:51], v[44:45], off
	v_add_u32_e32 v107, 0, v69
	s_waitcnt lgkmcnt(0)
	s_barrier
	v_add_u32_e32 v44, 0x1b600, v107
	ds_read2st64_b64 v[108:111], v44 offset1:1
	ds_read2st64_b64 v[112:115], v44 offset0:2 offset1:3
	ds_read2st64_b64 v[116:119], v44 offset0:4 offset1:5
	ds_read2st64_b64 v[120:123], v44 offset0:6 offset1:7
	v_lshlrev_b32_e32 v135, 16, v104
	v_and_b32_e32 v136, 0xffff0000, v104
	s_waitcnt lgkmcnt(3)
	v_cndmask_b32_e64 v124, 1.0, v108, s[8:9]
	v_cndmask_b32_e64 v125, 1.0, v109, s[8:9]
	v_cndmask_b32_e64 v126, 1.0, v110, s[10:11]
	v_cndmask_b32_e64 v127, 1.0, v111, s[10:11]
	v_pk_mul_f32 v[44:45], v[108:109], v[110:111]
	v_lshlrev_b32_e32 v137, 16, v105
	s_waitcnt lgkmcnt(2)
	v_pk_mul_f32 v[44:45], v[44:45], v[112:113]
	v_and_b32_e32 v138, 0xffff0000, v105
	v_pk_mul_f32 v[104:105], v[124:125], v[126:127]
	v_cndmask_b32_e64 v113, 1.0, v113, s[12:13]
	v_cndmask_b32_e64 v112, 1.0, v112, s[12:13]
	v_pk_mul_f32 v[104:105], v[104:105], v[112:113]
	v_cndmask_b32_e64 v113, 1.0, v115, s[6:7]
	v_cndmask_b32_e64 v112, 1.0, v114, s[6:7]
	v_pk_mul_f32 v[108:109], v[44:45], v[114:115]
	v_pk_mul_f32 v[104:105], v[104:105], v[112:113]
	s_waitcnt lgkmcnt(1)
	v_cndmask_b32_e64 v113, 1.0, v117, s[14:15]
	v_cndmask_b32_e64 v112, 1.0, v116, s[14:15]
	v_rcp_f32_e32 v110, v108
	v_rcp_f32_e32 v111, v109
	v_pk_mul_f32 v[104:105], v[104:105], v[112:113]
	v_cndmask_b32_e64 v113, 1.0, v119, s[16:17]
	v_cndmask_b32_e64 v112, 1.0, v118, s[16:17]
	v_pk_mul_f32 v[104:105], v[104:105], v[112:113]
	s_waitcnt lgkmcnt(0)
; #define LAS __attribute__((address_space(3)))
; __device__ __forceinline__ unsigned pkbf(float lo, float hi) { typedef __bf16 b2 __attribute__((ext_vector_type(2))); f32x2 v = {lo, hi}; b2 b = __builtin_convertvector(v, b2); return __builtin_bit_cast(unsigned, b); }
; __device__ __forceinline__ float bflo(unsigned u) { return __uint_as_float(u << 16); }
; __device__ __forceinline__ float bfhi(unsigned u) { return __uint_as_float(u & 0xffff0000u); }
; __device__ __forceinline__ void hgrn_phase(LAS unsigned char* lds, const bf16_t* mix, bf16_t* OFB, int item) {
;     ...
; #pragma unroll
;         for (int j = 0; j < 8; ++j) {
;             const float e10 = pr0 * c0[j], e11 = pr1 * c1[j];
;             const float e20 = __builtin_amdgcn_rcpf(e10), e21 = __builtin_amdgcn_rcpf(e11);
;             const float qi0 = bflo(cq[j]) * e10, qi1 = bfhi(cq[j]) * e11, ki0 = bflo(ck[j]) * e20, ki1 = bfhi(ck[j]) * e21;
;             const int ro = (8 * wid + j), co = 4 * lane;
;             *(LAS unsigned*)(lds + HG_QI + ro * HG_P + co) = pkbf(qi0, qi1);
;             *(LAS unsigned*)(lds + HG_KI + ro * HG_P + co) = pkbf(ki0, ki1);
;             *(LAS unsigned*)(lds + HG_QG + ro * HG_P + co) = pkbf(qi0 * eM0, qi1 * eM1);
;             *(LAS unsigned*)(lds + HG_KD + ro * HG_KDP + co) = pkbf(ki0 * eL0, ki1 * eL1);
;         }
;         *(LAS u32x4*)(lds + HG_V + tv * HG_VP + cv * 16) = cvv;
;         if (wid == 0) *(LAS f32x2*)(lds + HG_EGL + 8 * lane) = (f32x2){last0, last1};
	v_cndmask_b32_e64 v113, 1.0, v121, s[18:19]
	v_cndmask_b32_e64 v112, 1.0, v120, s[18:19]
	v_pk_mul_f32 v[44:45], v[108:109], v[116:117]
	v_pk_mul_f32 v[104:105], v[104:105], v[112:113]
	v_cndmask_b32_e64 v113, 1.0, v123, s[20:21]
	v_cndmask_b32_e64 v112, 1.0, v122, s[20:21]
	v_pk_mul_f32 v[44:45], v[44:45], v[118:119]
	v_pk_mul_f32 v[104:105], v[104:105], v[112:113]
	v_pk_mul_f32 v[44:45], v[44:45], v[120:121]
	v_pk_mul_f32 v[104:105], v[110:111], v[104:105]
	v_pk_mul_f32 v[44:45], v[44:45], v[122:123]
	v_pk_mul_f32 v[64:65], v[64:65], v[104:105]
	v_pk_mul_f32 v[128:129], v[110:111], v[44:45]
	v_rcp_f32_e32 v110, v64
	v_rcp_f32_e32 v111, v65
	v_lshlrev_b32_e32 v130, 16, v103
	v_and_b32_e32 v131, 0xffff0000, v103
	v_pk_mul_f32 v[64:65], v[64:65], v[130:131]
	v_lshlrev_b32_e32 v133, 16, v102
	v_and_b32_e32 v134, 0xffff0000, v102
	v_lshlrev_b32_e32 v102, 16, v100
	v_and_b32_e32 v103, 0xffff0000, v100
	v_pk_mul_f32 v[36:37], v[110:111], v[36:37]
	v_cvt_pk_bf16_f32 v100, v64, v65
	v_pk_mul_f32 v[64:65], v[108:109], v[64:65]
	v_add_u32_e32 v110, s67, v70
	v_cvt_pk_bf16_f32 v111, v36, v37
	v_cvt_pk_bf16_f32 v64, v64, v65
	v_pk_mul_f32 v[36:37], v[128:129], v[36:37]
	ds_write_b32 v110, v64 offset:34816
	v_cvt_pk_bf16_f32 v64, v36, v37
	v_pk_mul_f32 v[36:37], v[62:63], v[104:105]
	v_lshlrev_b32_e32 v132, 16, v101
	v_rcp_f32_e32 v62, v36
	v_rcp_f32_e32 v63, v37
	v_and_b32_e32 v101, 0xffff0000, v101
	v_add_u32_e32 v65, s62, v70
	ds_write2st64_b32 v110, v100, v111 offset1:68
	v_pk_mul_f32 v[34:35], v[62:63], v[34:35]
	ds_write_b32 v65, v64 offset:52224
	v_mul_f32_e32 v36, v36, v132
	v_mul_f32_e32 v37, v37, v101
	v_cvt_pk_bf16_f32 v64, v34, v35
	v_pk_mul_f32 v[34:35], v[128:129], v[34:35]
	v_cvt_pk_bf16_f32 v62, v36, v37
	v_pk_mul_f32 v[36:37], v[108:109], v[36:37]
	v_cvt_pk_bf16_f32 v100, v34, v35
	v_pk_mul_f32 v[34:35], v[60:61], v[104:105]
	v_cvt_pk_bf16_f32 v65, v36, v37
	v_rcp_f32_e32 v36, v34
	v_rcp_f32_e32 v37, v35
	s_mul_i32 s56, s68, 0x110
	v_mul_f32_e32 v34, v34, v133
	v_mul_f32_e32 v35, v35, v134
	v_add_u32_e32 v63, s56, v70
	v_pk_mul_f32 v[32:33], v[36:37], v[32:33]
	v_cvt_pk_bf16_f32 v36, v34, v35
	ds_write2_b32 v63, v62, v36 offset1:68
	v_cvt_pk_bf16_f32 v36, v32, v33
	v_add_u32_e32 v37, 0x4400, v63
	v_pk_mul_f32 v[34:35], v[108:109], v[34:35]
	v_pk_mul_f32 v[32:33], v[128:129], v[32:33]
	ds_write2_b32 v37, v64, v36 offset1:68
	v_cvt_pk_bf16_f32 v34, v34, v35
	v_add_u32_e32 v36, 0x8800, v63
	v_cvt_pk_bf16_f32 v61, v32, v33
	v_pk_mul_f32 v[32:33], v[58:59], v[104:105]
	ds_write2_b32 v36, v65, v34 offset1:68
	v_rcp_f32_e32 v34, v32
	v_rcp_f32_e32 v35, v33
	v_mul_f32_e32 v32, v32, v135
	v_mul_f32_e32 v33, v33, v136
	s_mul_i32 s56, s68, 0x140
	v_pk_mul_f32 v[14:15], v[34:35], v[14:15]
	v_cvt_pk_bf16_f32 v34, v32, v33
	v_cvt_pk_bf16_f32 v35, v14, v15
	v_pk_mul_f32 v[14:15], v[128:129], v[14:15]
	v_pk_mul_f32 v[32:33], v[108:109], v[32:33]
	v_cvt_pk_bf16_f32 v59, v14, v15
	v_pk_mul_f32 v[14:15], v[46:47], v[104:105]
	v_cvt_pk_bf16_f32 v58, v32, v33
	v_rcp_f32_e32 v32, v14
	v_rcp_f32_e32 v33, v15
	v_mul_f32_e32 v14, v14, v137
	v_mul_f32_e32 v15, v15, v138
	v_add_u32_e32 v60, s56, v70
	v_pk_mul_f32 v[12:13], v[32:33], v[12:13]
	v_cvt_pk_bf16_f32 v32, v14, v15
	v_pk_mul_f32 v[14:15], v[108:109], v[14:15]
	v_add_u32_e32 v62, 0xcc00, v60
	v_cvt_pk_bf16_f32 v14, v14, v15
	ds_write2_b32 v62, v100, v61 offset1:80
	ds_write_b32 v60, v59 offset:52864
	ds_write2_b32 v63, v34, v32 offset0:136 offset1:204
	v_cvt_pk_bf16_f32 v32, v12, v13
	ds_write2_b32 v36, v58, v14 offset0:136 offset1:204
	v_pk_mul_f32 v[14:15], v[42:43], v[104:105]
	ds_write2_b32 v37, v35, v32 offset0:136 offset1:204
	v_rcp_f32_e32 v32, v14
	v_rcp_f32_e32 v33, v15
	v_lshlrev_b32_e32 v139, 16, v106
	v_and_b32_e32 v106, 0xffff0000, v106
	v_pk_mul_f32 v[12:13], v[128:129], v[12:13]
	v_pk_mul_f32 v[10:11], v[32:33], v[10:11]
	v_cvt_pk_bf16_f32 v34, v12, v13
	v_mul_f32_e32 v12, v14, v139
	v_mul_f32_e32 v13, v15, v106
	v_cvt_pk_bf16_f32 v15, v10, v11
	v_pk_mul_f32 v[10:11], v[128:129], v[10:11]
	v_cvt_pk_bf16_f32 v14, v12, v13
	v_pk_mul_f32 v[12:13], v[108:109], v[12:13]
	v_cvt_pk_bf16_f32 v33, v10, v11
	v_pk_mul_f32 v[10:11], v[40:41], v[104:105]
	v_cvt_pk_bf16_f32 v32, v12, v13
	v_rcp_f32_e32 v12, v10
	v_rcp_f32_e32 v13, v11
	v_pk_mul_f32 v[10:11], v[10:11], v[102:103]
	v_add_u32_e32 v35, 0xce00, v60
	s_andn2_b64 vcc, exec, s[58:59]
	v_pk_mul_f32 v[8:9], v[12:13], v[8:9]
	v_cvt_pk_bf16_f32 v12, v10, v11
	v_add_u32_e32 v13, 0x400, v63
	ds_write2_b32 v13, v14, v12 offset0:16 offset1:84
	v_cvt_pk_bf16_f32 v12, v8, v9
	v_pk_mul_f32 v[10:11], v[108:109], v[10:11]
	v_pk_mul_f32 v[8:9], v[128:129], v[8:9]
	v_cvt_pk_bf16_f32 v10, v10, v11
	v_add_u32_e32 v11, 0x8c00, v63
	v_cvt_pk_bf16_f32 v14, v8, v9
	v_pk_mul_f32 v[8:9], v[38:39], v[104:105]
	ds_write2_b32 v11, v32, v10 offset0:16 offset1:84
	v_rcp_f32_e32 v10, v8
	v_rcp_f32_e32 v11, v9
	v_add_u32_e32 v13, 0x4800, v63
	ds_write2_b32 v13, v15, v12 offset0:16 offset1:84
	v_lshlrev_b32_e32 v12, 16, v1
	v_and_b32_e32 v13, 0xffff0000, v1
	v_pk_mul_f32 v[8:9], v[8:9], v[12:13]
	v_pk_mul_f32 v[6:7], v[10:11], v[6:7]
	v_cvt_pk_bf16_f32 v1, v8, v9
	ds_write_b32 v63, v1 offset:1632
	v_cvt_pk_bf16_f32 v1, v6, v7
	v_pk_mul_f32 v[8:9], v[108:109], v[8:9]
	ds_write_b32 v63, v1 offset:19040
	v_cvt_pk_bf16_f32 v1, v8, v9
	v_pk_mul_f32 v[6:7], v[128:129], v[6:7]
	ds_write_b32 v63, v1 offset:36448
	v_cvt_pk_bf16_f32 v1, v6, v7
	v_add_u32_e32 v6, 0xd000, v60
	ds_write2_b32 v35, v34, v33 offset0:112 offset1:192
	ds_write2_b32 v6, v14, v1 offset0:144 offset1:224
	s_waitcnt vmcnt(17)
	ds_write_b128 v81, v[2:5]
	s_cbranch_vccnz .LBB0_513
	v_add_u32_e32 v1, 0x1b400, v107
	ds_write_b64 v1, v[44:45]
